# ln_in phase: 8 row loads issued together per batch instead of one load per vmcnt(0); on top of LN g/b from LDS and GEMM unit-boundary edits
# speedup vs baseline: 1.0024x; 1.0007x over previous
; __device__ __forceinline__ int ltid() { int t = threadIdx.x; asm volatile("" : "+v"(t)); return t; }
; __device__ __forceinline__ int lbid() { int b = blockIdx.x; asm volatile("" : "+s"(b)); return b; }
; template <int NR>
; __device__ __forceinline__ void ln_in_rows(const float* const (&sp)[NR], bool zero_src, bf16_t* h, const float* g, const float* b, int lane) {
;     f32x4 v[NR][4][2]; float sm[NR];
; #pragma unroll
;     for (int i = 0; i < NR; ++i)
; #pragma unroll
;         for (int j = 0; j < 4; ++j)
; #pragma unroll
;             for (int e = 0; e < 2; ++e) v[i][j][e] = zero_src ? (f32x4){0.f, 0.f, 0.f, 0.f} : *(const f32x4*)(sp[i] + 8 * lane + 512 * j + 4 * e);
; __device__ __forceinline__ void ln_in_phase(const Args& a) {
;     const int tid = ltid(), lane = tid & 63, gw = lbid() * 8 + (tid >> 6), NGW = gridDim.x * 8;
;     bf16_t* hb = (bf16_t*)(a.ws + WS_HB); f32x2* st = (f32x2*)(a.ws + WS_ST);
;     for (int r = 4 * gw; r < TP; r += 4 * NGW)
;       { const float* const sp[4] = {in_row(a, r), in_row(a, r + 1), in_row(a, r + 2), in_row(a, r + 3)};
;         ln_in_rows<4>(sp, r >= TREAL, hb + (size_t)r * D, a.in[3], a.in[4], lane); }
.LBB0_527:
	s_andn2_saveexec_b64 s[0:1], s[0:1]
	s_mov_b64 s[4:5], 0x6000
	v_lshl_add_u64 v[150:151], v[122:123], 0, s[4:5]
	s_or_b64 exec, exec, s[0:1]
	s_mov_b32 s0, 0xc140
	v_cmp_gt_i32_e64 s[40:41], s0, v2
	v_mov_b32_e32 v143, 0
	s_waitcnt vmcnt(0)
	v_lshlrev_b32_e32 v70, 2, v106
	v_mov_b32_e32 v142, 0
	v_mov_b32_e32 v146, 0
	v_mov_b32_e32 v92, 0
	v_mov_b32_e32 v144, 0
	s_and_saveexec_b64 s[0:1], s[40:41]
	s_cbranch_execz .Lmy_lnin_b0
	v_mov_b32_e32 v71, v0
	v_lshl_add_u64 v[248:249], v[26:27], 0, v[70:71]
	global_load_dwordx4 v[216:219], v[248:249], off
	v_lshl_add_u64 v[248:249], v[26:27], 0, v[70:71]
	global_load_dwordx4 v[220:223], v[248:249], off offset:16
	v_lshl_add_u64 v[248:249], v[26:27], 0, v[70:71]
	global_load_dwordx4 v[224:227], v[248:249], off offset:2048
	v_lshl_add_u64 v[248:249], v[26:27], 0, v[70:71]
	global_load_dwordx4 v[228:231], v[248:249], off offset:2064
	v_lshl_add_u64 v[248:249], v[26:27], 0, v[70:71]
	v_add_co_u32_e32 v248, vcc, 0x1000, v248
	s_nop 1
	v_addc_co_u32_e32 v249, vcc, 0, v249, vcc
	global_load_dwordx4 v[232:235], v[248:249], off
	v_lshl_add_u64 v[248:249], v[26:27], 0, v[70:71]
	v_add_co_u32_e32 v248, vcc, 0x1000, v248
	s_nop 1
	v_addc_co_u32_e32 v249, vcc, 0, v249, vcc
	global_load_dwordx4 v[236:239], v[248:249], off offset:16
	v_lshl_add_u64 v[248:249], v[26:27], 0, v[70:71]
	v_add_co_u32_e32 v248, vcc, 0x1000, v248
	s_nop 1
	v_addc_co_u32_e32 v249, vcc, 0, v249, vcc
	global_load_dwordx4 v[240:243], v[248:249], off offset:2048
	v_lshl_add_u64 v[248:249], v[26:27], 0, v[70:71]
	v_add_co_u32_e32 v248, vcc, 0x1000, v248
	s_nop 1
	v_addc_co_u32_e32 v249, vcc, 0, v249, vcc
	global_load_dwordx4 v[244:247], v[248:249], off offset:2064
.Lmy_lnin_b0:
	s_or_b64 exec, exec, s[0:1]
	s_waitcnt vmcnt(0)
	s_and_saveexec_b64 s[0:1], s[40:41]
	s_cbranch_execz .LBB0_531
	v_mov_b32_e32 v71, v0
	v_mov_b32_e32 v90, v216
	v_mov_b32_e32 v91, v217
	v_mov_b32_e32 v92, v218
	v_mov_b32_e32 v93, v219
	v_mov_b32_e32 v142, v90
	v_mov_b32_e32 v146, v91
	v_mov_b32_e32 v144, v93
.LBB0_531:
	s_or_b64 exec, exec, s[0:1]
	v_mov_b32_e32 v147, 0
	v_mov_b32_e32 v93, 0
	v_mov_b32_e32 v145, 0
	s_and_saveexec_b64 s[0:1], s[40:41]
	s_cbranch_execz .LBB0_533
	v_mov_b32_e32 v71, v0
	v_mov_b32_e32 v2, v220
	v_mov_b32_e32 v3, v221
	v_mov_b32_e32 v4, v222
	v_mov_b32_e32 v5, v223
	v_mov_b32_e32 v143, v2
	v_mov_b32_e32 v147, v3
	v_mov_b32_e32 v93, v4
	v_mov_b32_e32 v145, v5
.LBB0_533:
	s_or_b64 exec, exec, s[0:1]
	v_mov_b32_e32 v18, 0
	v_mov_b32_e32 v22, 0
	v_mov_b32_e32 v148, 0
	v_mov_b32_e32 v149, 0
	v_mov_b32_e32 v23, 0
	s_and_saveexec_b64 s[0:1], s[40:41]
	s_cbranch_execz .LBB0_535
	v_mov_b32_e32 v71, v0
	v_mov_b32_e32 v22, v224
	v_mov_b32_e32 v23, v225
	v_mov_b32_e32 v24, v226
	v_mov_b32_e32 v25, v227
	v_mov_b32_e32 v148, v23
	v_mov_b32_e32 v149, v24
	v_mov_b32_e32 v23, v25
.LBB0_535:
	s_or_b64 exec, exec, s[0:1]
	v_mov_b32_e32 v19, 0
	v_mov_b32_e32 v20, 0
	v_mov_b32_e32 v21, 0
	s_and_saveexec_b64 s[0:1], s[40:41]
	s_cbranch_execz .LBB0_537
	v_mov_b32_e32 v71, v0
	v_mov_b32_e32 v18, v228
	v_mov_b32_e32 v19, v229
	v_mov_b32_e32 v20, v230
	v_mov_b32_e32 v21, v231
.LBB0_537:
	s_or_b64 exec, exec, s[0:1]
	v_mov_b32_e32 v10, 0
	v_mov_b32_e32 v127, 0
	v_mov_b32_e32 v15, 0
	v_mov_b32_e32 v129, 0
	v_mov_b32_e32 v17, 0
	s_and_saveexec_b64 s[0:1], s[40:41]
	s_cbranch_execz .LBB0_539
	v_mov_b32_e32 v71, v0
	v_mov_b32_e32 v14, v232
	v_mov_b32_e32 v15, v233
	v_mov_b32_e32 v16, v234
	v_mov_b32_e32 v17, v235
	v_mov_b32_e32 v127, v14
	v_mov_b32_e32 v129, v16
.LBB0_539:
	s_or_b64 exec, exec, s[0:1]
	v_mov_b32_e32 v162, 0
	v_mov_b32_e32 v163, 0
	v_mov_b32_e32 v11, 0
	s_and_saveexec_b64 s[0:1], s[40:41]
	s_cbranch_execz .LBB0_541
	v_mov_b32_e32 v71, v0
	v_mov_b32_e32 v10, v236
	v_mov_b32_e32 v11, v237
	v_mov_b32_e32 v12, v238
	v_mov_b32_e32 v13, v239
	v_mov_b32_e32 v162, v11
	v_mov_b32_e32 v163, v12
	v_mov_b32_e32 v11, v13
.LBB0_541:
	s_or_b64 exec, exec, s[0:1]
	v_mov_b32_e32 v2, 0
	v_mov_b32_e32 v6, 0
	v_mov_b32_e32 v7, 0
	v_mov_b32_e32 v8, 0
	v_mov_b32_e32 v9, 0
	s_and_saveexec_b64 s[0:1], s[40:41]
	s_cbranch_execz .LBB0_543
	v_mov_b32_e32 v71, v0
	v_mov_b32_e32 v6, v240
	v_mov_b32_e32 v7, v241
	v_mov_b32_e32 v8, v242
	v_mov_b32_e32 v9, v243
.LBB0_543:
	s_or_b64 exec, exec, s[0:1]
	v_mov_b32_e32 v3, 0
	v_mov_b32_e32 v13, 0
	v_mov_b32_e32 v5, 0
	s_and_saveexec_b64 s[0:1], s[40:41]
	s_cbranch_execz .LBB0_545
	v_mov_b32_e32 v71, v0
	v_mov_b32_e32 v2, v244
	v_mov_b32_e32 v3, v245
	v_mov_b32_e32 v4, v246
	v_mov_b32_e32 v5, v247
	v_mov_b32_e32 v13, v4
.LBB0_545:
	s_or_b64 exec, exec, s[0:1]
	v_mov_b32_e32 v167, 0
	v_mov_b32_e32 v166, 0
	v_mov_b32_e32 v168, 0
	v_mov_b32_e32 v96, 0
	v_mov_b32_e32 v94, 0
	s_and_saveexec_b64 s[0:1], s[40:41]
	s_cbranch_execz .Lmy_lnin_b1
	v_mov_b32_e32 v71, v0
	v_lshl_add_u64 v[248:249], v[48:49], 0, v[70:71]
	global_load_dwordx4 v[216:219], v[248:249], off
	v_lshl_add_u64 v[248:249], v[48:49], 0, v[70:71]
	global_load_dwordx4 v[220:223], v[248:249], off offset:16
	v_lshl_add_u64 v[248:249], v[48:49], 0, v[70:71]
	global_load_dwordx4 v[224:227], v[248:249], off offset:2048
	v_lshl_add_u64 v[248:249], v[48:49], 0, v[70:71]
	global_load_dwordx4 v[228:231], v[248:249], off offset:2064
	v_lshl_add_u64 v[248:249], v[48:49], 0, v[70:71]
	v_add_co_u32_e32 v248, vcc, 0x1000, v248
	s_nop 1
	v_addc_co_u32_e32 v249, vcc, 0, v249, vcc
	global_load_dwordx4 v[232:235], v[248:249], off
	v_lshl_add_u64 v[248:249], v[48:49], 0, v[70:71]
	v_add_co_u32_e32 v248, vcc, 0x1000, v248
	s_nop 1
	v_addc_co_u32_e32 v249, vcc, 0, v249, vcc
	global_load_dwordx4 v[236:239], v[248:249], off offset:16
	v_lshl_add_u64 v[248:249], v[48:49], 0, v[70:71]
	v_add_co_u32_e32 v248, vcc, 0x1000, v248
	s_nop 1
	v_addc_co_u32_e32 v249, vcc, 0, v249, vcc
	global_load_dwordx4 v[240:243], v[248:249], off offset:2048
	v_lshl_add_u64 v[248:249], v[48:49], 0, v[70:71]
	v_add_co_u32_e32 v248, vcc, 0x1000, v248
	s_nop 1
	v_addc_co_u32_e32 v249, vcc, 0, v249, vcc
	global_load_dwordx4 v[244:247], v[248:249], off offset:2064
; template <int NR>
; __device__ __forceinline__ void ln_in_rows(const float* const (&sp)[NR], bool zero_src, bf16_t* h, const float* g, const float* b, int lane) {
;     f32x4 v[NR][4][2]; float sm[NR];
; #pragma unroll
;     for (int i = 0; i < NR; ++i)
; #pragma unroll
;         for (int j = 0; j < 4; ++j)
; #pragma unroll
;             for (int e = 0; e < 2; ++e) v[i][j][e] = zero_src ? (f32x4){0.f, 0.f, 0.f, 0.f} : *(const f32x4*)(sp[i] + 8 * lane + 512 * j + 4 * e);
.Lmy_lnin_b1:
	s_or_b64 exec, exec, s[0:1]
	s_waitcnt vmcnt(0)
	s_and_saveexec_b64 s[0:1], s[40:41]
	s_cbranch_execz .LBB0_547
	v_mov_b32_e32 v71, v0
	v_mov_b32_e32 v94, v216
	v_mov_b32_e32 v95, v217
	v_mov_b32_e32 v96, v218
	v_mov_b32_e32 v97, v219
	v_mov_b32_e32 v166, v94
	v_mov_b32_e32 v168, v95
	v_mov_b32_e32 v94, v97
.LBB0_547:
	s_or_b64 exec, exec, s[0:1]
	v_mov_b32_e32 v169, 0
	v_mov_b32_e32 v97, 0
	v_mov_b32_e32 v95, 0
	s_and_saveexec_b64 s[0:1], s[40:41]
	s_cbranch_execz .LBB0_549
	v_mov_b32_e32 v71, v0
	v_mov_b32_e32 v24, v220
	v_mov_b32_e32 v25, v221
	v_mov_b32_e32 v26, v222
	v_mov_b32_e32 v27, v223
	v_mov_b32_e32 v167, v24
	v_mov_b32_e32 v169, v25
	v_mov_b32_e32 v97, v26
	v_mov_b32_e32 v95, v27
.LBB0_549:
	s_or_b64 exec, exec, s[0:1]
	v_mov_b32_e32 v40, 0
	v_mov_b32_e32 v44, 0
	v_mov_b32_e32 v170, 0
	v_mov_b32_e32 v171, 0
	v_mov_b32_e32 v45, 0
	s_and_saveexec_b64 s[0:1], s[40:41]
	s_cbranch_execz .LBB0_551
	v_mov_b32_e32 v71, v0
	v_mov_b32_e32 v44, v224
	v_mov_b32_e32 v45, v225
	v_mov_b32_e32 v46, v226
	v_mov_b32_e32 v47, v227
	v_mov_b32_e32 v170, v45
	v_mov_b32_e32 v171, v46
	v_mov_b32_e32 v45, v47
.LBB0_551:
	s_or_b64 exec, exec, s[0:1]
	v_mov_b32_e32 v41, 0
	v_mov_b32_e32 v42, 0
	v_mov_b32_e32 v43, 0
	s_and_saveexec_b64 s[0:1], s[40:41]
	s_cbranch_execz .LBB0_553
	v_mov_b32_e32 v71, v0
	v_mov_b32_e32 v40, v228
	v_mov_b32_e32 v41, v229
	v_mov_b32_e32 v42, v230
	v_mov_b32_e32 v43, v231
.LBB0_553:
	s_or_b64 exec, exec, s[0:1]
	v_mov_b32_e32 v32, 0
	v_mov_b32_e32 v131, 0
	v_mov_b32_e32 v37, 0
	v_mov_b32_e32 v133, 0
	v_mov_b32_e32 v39, 0
	s_and_saveexec_b64 s[0:1], s[40:41]
	s_cbranch_execz .LBB0_555
	v_mov_b32_e32 v71, v0
	v_mov_b32_e32 v36, v232
	v_mov_b32_e32 v37, v233
	v_mov_b32_e32 v38, v234
	v_mov_b32_e32 v39, v235
	v_mov_b32_e32 v131, v36
	v_mov_b32_e32 v133, v38
.LBB0_555:
	s_or_b64 exec, exec, s[0:1]
	v_mov_b32_e32 v172, 0
	v_mov_b32_e32 v173, 0
	v_mov_b32_e32 v33, 0
	s_and_saveexec_b64 s[0:1], s[40:41]
	s_cbranch_execz .LBB0_557
	v_mov_b32_e32 v71, v0
	v_mov_b32_e32 v32, v236
	v_mov_b32_e32 v33, v237
	v_mov_b32_e32 v34, v238
	v_mov_b32_e32 v35, v239
	v_mov_b32_e32 v172, v33
	v_mov_b32_e32 v173, v34
	v_mov_b32_e32 v33, v35
.LBB0_557:
	s_or_b64 exec, exec, s[0:1]
	v_mov_b32_e32 v24, 0
	v_mov_b32_e32 v28, 0
	v_mov_b32_e32 v29, 0
	v_mov_b32_e32 v30, 0
	v_mov_b32_e32 v31, 0
	s_and_saveexec_b64 s[0:1], s[40:41]
	s_cbranch_execz .LBB0_559
	v_mov_b32_e32 v71, v0
	v_mov_b32_e32 v28, v240
	v_mov_b32_e32 v29, v241
	v_mov_b32_e32 v30, v242
	v_mov_b32_e32 v31, v243
.LBB0_559:
	s_or_b64 exec, exec, s[0:1]
	v_mov_b32_e32 v25, 0
	v_mov_b32_e32 v35, 0
	v_mov_b32_e32 v27, 0
	s_and_saveexec_b64 s[0:1], s[40:41]
	s_cbranch_execz .LBB0_561
	v_mov_b32_e32 v71, v0
	v_mov_b32_e32 v24, v244
	v_mov_b32_e32 v25, v245
	v_mov_b32_e32 v26, v246
	v_mov_b32_e32 v27, v247
	v_mov_b32_e32 v35, v26
.LBB0_561:
	s_or_b64 exec, exec, s[0:1]
	v_mov_b32_e32 v175, 0
	v_mov_b32_e32 v174, 0
	v_mov_b32_e32 v178, 0
	v_mov_b32_e32 v100, 0
	v_mov_b32_e32 v98, 0
	s_and_saveexec_b64 s[0:1], s[40:41]
	s_cbranch_execz .Lmy_lnin_b2
	v_mov_b32_e32 v71, v0
	v_lshl_add_u64 v[248:249], v[72:73], 0, v[70:71]
	global_load_dwordx4 v[216:219], v[248:249], off
	v_lshl_add_u64 v[248:249], v[72:73], 0, v[70:71]
	global_load_dwordx4 v[220:223], v[248:249], off offset:16
	v_lshl_add_u64 v[248:249], v[72:73], 0, v[70:71]
	global_load_dwordx4 v[224:227], v[248:249], off offset:2048
	v_lshl_add_u64 v[248:249], v[72:73], 0, v[70:71]
	global_load_dwordx4 v[228:231], v[248:249], off offset:2064
	v_lshl_add_u64 v[248:249], v[72:73], 0, v[70:71]
	v_add_co_u32_e32 v248, vcc, 0x1000, v248
	s_nop 1
	v_addc_co_u32_e32 v249, vcc, 0, v249, vcc
	global_load_dwordx4 v[232:235], v[248:249], off
	v_lshl_add_u64 v[248:249], v[72:73], 0, v[70:71]
	v_add_co_u32_e32 v248, vcc, 0x1000, v248
	s_nop 1
	v_addc_co_u32_e32 v249, vcc, 0, v249, vcc
	global_load_dwordx4 v[236:239], v[248:249], off offset:16
	v_lshl_add_u64 v[248:249], v[72:73], 0, v[70:71]
	v_add_co_u32_e32 v248, vcc, 0x1000, v248
	s_nop 1
	v_addc_co_u32_e32 v249, vcc, 0, v249, vcc
	global_load_dwordx4 v[240:243], v[248:249], off offset:2048
	v_lshl_add_u64 v[248:249], v[72:73], 0, v[70:71]
	v_add_co_u32_e32 v248, vcc, 0x1000, v248
	s_nop 1
	v_addc_co_u32_e32 v249, vcc, 0, v249, vcc
	global_load_dwordx4 v[244:247], v[248:249], off offset:2064
.Lmy_lnin_b2:
	s_or_b64 exec, exec, s[0:1]
	s_waitcnt vmcnt(0)
	s_and_saveexec_b64 s[0:1], s[40:41]
	s_cbranch_execz .LBB0_563
	v_mov_b32_e32 v71, v0
	v_mov_b32_e32 v98, v216
	v_mov_b32_e32 v99, v217
	v_mov_b32_e32 v100, v218
	v_mov_b32_e32 v101, v219
	v_mov_b32_e32 v174, v98
	v_mov_b32_e32 v178, v99
	v_mov_b32_e32 v98, v101
.LBB0_563:
	s_or_b64 exec, exec, s[0:1]
	v_mov_b32_e32 v179, 0
	v_mov_b32_e32 v101, 0
	v_mov_b32_e32 v99, 0
	s_and_saveexec_b64 s[0:1], s[40:41]
	s_cbranch_execz .LBB0_565
	v_mov_b32_e32 v71, v0
	v_mov_b32_e32 v46, v220
	v_mov_b32_e32 v47, v221
	v_mov_b32_e32 v48, v222
	v_mov_b32_e32 v49, v223
	v_mov_b32_e32 v175, v46
	v_mov_b32_e32 v179, v47
	v_mov_b32_e32 v101, v48
	v_mov_b32_e32 v99, v49
.LBB0_565:
	s_or_b64 exec, exec, s[0:1]
	v_mov_b32_e32 v62, 0
	v_mov_b32_e32 v66, 0
	v_mov_b32_e32 v182, 0
	v_mov_b32_e32 v183, 0
	v_mov_b32_e32 v67, 0
	s_and_saveexec_b64 s[0:1], s[40:41]
	s_cbranch_execz .LBB0_567
	v_mov_b32_e32 v71, v0
	v_mov_b32_e32 v66, v224
	v_mov_b32_e32 v67, v225
	v_mov_b32_e32 v68, v226
	v_mov_b32_e32 v69, v227
	v_mov_b32_e32 v182, v67
	v_mov_b32_e32 v183, v68
	v_mov_b32_e32 v67, v69
.LBB0_567:
	s_or_b64 exec, exec, s[0:1]
	v_mov_b32_e32 v63, 0
	v_mov_b32_e32 v64, 0
	v_mov_b32_e32 v65, 0
	s_and_saveexec_b64 s[0:1], s[40:41]
	s_cbranch_execz .LBB0_569
	v_mov_b32_e32 v71, v0
	v_mov_b32_e32 v62, v228
	v_mov_b32_e32 v63, v229
	v_mov_b32_e32 v64, v230
	v_mov_b32_e32 v65, v231
; template <int NR>
; __device__ __forceinline__ void ln_in_rows(const float* const (&sp)[NR], bool zero_src, bf16_t* h, const float* g, const float* b, int lane) {
;     f32x4 v[NR][4][2]; float sm[NR];
; #pragma unroll
;     for (int i = 0; i < NR; ++i)
; #pragma unroll
;         for (int j = 0; j < 4; ++j)
; #pragma unroll
;             for (int e = 0; e < 2; ++e) v[i][j][e] = zero_src ? (f32x4){0.f, 0.f, 0.f, 0.f} : *(const f32x4*)(sp[i] + 8 * lane + 512 * j + 4 * e);
; __device__ __forceinline__ void ln_in_phase(const Args& a) {
;     ...
;     for (int r = 4 * gw; r < TP; r += 4 * NGW)
;       { const float* const sp[4] = {in_row(a, r), in_row(a, r + 1), in_row(a, r + 2), in_row(a, r + 3)};
;         ln_in_rows<4>(sp, r >= TREAL, hb + (size_t)r * D, a.in[3], a.in[4], lane); }
.LBB0_569:
	s_or_b64 exec, exec, s[0:1]
	v_mov_b32_e32 v54, 0
	v_mov_b32_e32 v135, 0
	v_mov_b32_e32 v59, 0
	v_mov_b32_e32 v137, 0
	v_mov_b32_e32 v61, 0
	s_and_saveexec_b64 s[0:1], s[40:41]
	s_cbranch_execz .LBB0_571
	v_mov_b32_e32 v71, v0
	v_mov_b32_e32 v58, v232
	v_mov_b32_e32 v59, v233
	v_mov_b32_e32 v60, v234
	v_mov_b32_e32 v61, v235
	v_mov_b32_e32 v135, v58
	v_mov_b32_e32 v137, v60
.LBB0_571:
	s_or_b64 exec, exec, s[0:1]
	v_mov_b32_e32 v184, 0
	v_mov_b32_e32 v185, 0
	v_mov_b32_e32 v55, 0
	s_and_saveexec_b64 s[0:1], s[40:41]
	s_cbranch_execz .LBB0_573
	v_mov_b32_e32 v71, v0
	v_mov_b32_e32 v54, v236
	v_mov_b32_e32 v55, v237
	v_mov_b32_e32 v56, v238
	v_mov_b32_e32 v57, v239
	v_mov_b32_e32 v184, v55
	v_mov_b32_e32 v185, v56
	v_mov_b32_e32 v55, v57
.LBB0_573:
	s_or_b64 exec, exec, s[0:1]
	v_mov_b32_e32 v46, 0
	v_mov_b32_e32 v50, 0
	v_mov_b32_e32 v51, 0
	v_mov_b32_e32 v52, 0
	v_mov_b32_e32 v53, 0
	s_and_saveexec_b64 s[0:1], s[40:41]
	s_cbranch_execz .LBB0_575
	v_mov_b32_e32 v71, v0
	v_mov_b32_e32 v50, v240
	v_mov_b32_e32 v51, v241
	v_mov_b32_e32 v52, v242
	v_mov_b32_e32 v53, v243
.LBB0_575:
	s_or_b64 exec, exec, s[0:1]
	v_mov_b32_e32 v47, 0
	v_mov_b32_e32 v57, 0
	v_mov_b32_e32 v49, 0
	s_and_saveexec_b64 s[0:1], s[40:41]
	s_cbranch_execz .LBB0_577
	v_mov_b32_e32 v71, v0
	v_mov_b32_e32 v46, v244
	v_mov_b32_e32 v47, v245
	v_mov_b32_e32 v48, v246
	v_mov_b32_e32 v49, v247
	v_mov_b32_e32 v57, v48
.LBB0_577:
	s_or_b64 exec, exec, s[0:1]
	v_mov_b32_e32 v187, 0
	v_mov_b32_e32 v186, 0
	v_mov_b32_e32 v188, 0
	v_mov_b32_e32 v104, 0
	v_mov_b32_e32 v102, 0
	s_and_saveexec_b64 s[0:1], s[40:41]
	s_cbranch_execz .Lmy_lnin_b3
	v_mov_b32_e32 v71, v0
	v_lshl_add_u64 v[248:249], v[150:151], 0, v[70:71]
	global_load_dwordx4 v[216:219], v[248:249], off
	v_lshl_add_u64 v[248:249], v[150:151], 0, v[70:71]
	global_load_dwordx4 v[220:223], v[248:249], off offset:16
	v_lshl_add_u64 v[248:249], v[150:151], 0, v[70:71]
	global_load_dwordx4 v[224:227], v[248:249], off offset:2048
	v_lshl_add_u64 v[248:249], v[150:151], 0, v[70:71]
	global_load_dwordx4 v[228:231], v[248:249], off offset:2064
	v_lshl_add_u64 v[248:249], v[150:151], 0, v[70:71]
	v_add_co_u32_e32 v248, vcc, 0x1000, v248
	s_nop 1
	v_addc_co_u32_e32 v249, vcc, 0, v249, vcc
	global_load_dwordx4 v[232:235], v[248:249], off
	v_lshl_add_u64 v[248:249], v[150:151], 0, v[70:71]
	v_add_co_u32_e32 v248, vcc, 0x1000, v248
	s_nop 1
	v_addc_co_u32_e32 v249, vcc, 0, v249, vcc
	global_load_dwordx4 v[236:239], v[248:249], off offset:16
	v_lshl_add_u64 v[248:249], v[150:151], 0, v[70:71]
	v_add_co_u32_e32 v248, vcc, 0x1000, v248
	s_nop 1
	v_addc_co_u32_e32 v249, vcc, 0, v249, vcc
	global_load_dwordx4 v[240:243], v[248:249], off offset:2048
	v_lshl_add_u64 v[248:249], v[150:151], 0, v[70:71]
	v_add_co_u32_e32 v248, vcc, 0x1000, v248
	s_nop 1
	v_addc_co_u32_e32 v249, vcc, 0, v249, vcc
	global_load_dwordx4 v[244:247], v[248:249], off offset:2064
.Lmy_lnin_b3:
	s_or_b64 exec, exec, s[0:1]
	s_waitcnt vmcnt(0)
	s_and_saveexec_b64 s[0:1], s[40:41]
	s_cbranch_execz .LBB0_579
	v_mov_b32_e32 v71, v0
	v_mov_b32_e32 v102, v216
	v_mov_b32_e32 v103, v217
	v_mov_b32_e32 v104, v218
	v_mov_b32_e32 v105, v219
	v_mov_b32_e32 v186, v102
	v_mov_b32_e32 v188, v103
	v_mov_b32_e32 v102, v105
.LBB0_579:
	s_or_b64 exec, exec, s[0:1]
	v_mov_b32_e32 v189, 0
	v_mov_b32_e32 v105, 0
	v_mov_b32_e32 v103, 0
	s_and_saveexec_b64 s[0:1], s[40:41]
	s_cbranch_execz .LBB0_581
	v_mov_b32_e32 v71, v0
	v_mov_b32_e32 v72, v220
	v_mov_b32_e32 v73, v221
	v_mov_b32_e32 v74, v222
	v_mov_b32_e32 v75, v223
	v_mov_b32_e32 v187, v72
	v_mov_b32_e32 v189, v73
	v_mov_b32_e32 v105, v74
	v_mov_b32_e32 v103, v75
.LBB0_581:
	s_or_b64 exec, exec, s[0:1]
	v_mov_b32_e32 v84, 0
	v_mov_b32_e32 v88, 0
	v_mov_b32_e32 v190, 0
	v_mov_b32_e32 v191, 0
	v_mov_b32_e32 v89, 0
	s_and_saveexec_b64 s[0:1], s[40:41]
	s_cbranch_execz .LBB0_583
	v_mov_b32_e32 v71, v0
	v_mov_b32_e32 v88, v224
	v_mov_b32_e32 v89, v225
	v_mov_b32_e32 v90, v226
	v_mov_b32_e32 v91, v227
	v_mov_b32_e32 v190, v89
	v_mov_b32_e32 v191, v90
	v_mov_b32_e32 v89, v91
.LBB0_583:
	s_or_b64 exec, exec, s[0:1]
	v_mov_b32_e32 v85, 0
	v_mov_b32_e32 v86, 0
	v_mov_b32_e32 v87, 0
	s_and_saveexec_b64 s[0:1], s[40:41]
	s_cbranch_execz .LBB0_585
	v_mov_b32_e32 v71, v0
	v_mov_b32_e32 v84, v228
	v_mov_b32_e32 v85, v229
	v_mov_b32_e32 v86, v230
	v_mov_b32_e32 v87, v231
.LBB0_585:
	s_or_b64 exec, exec, s[0:1]
	v_mov_b32_e32 v76, 0
	v_mov_b32_e32 v139, 0
	v_mov_b32_e32 v81, 0
	v_mov_b32_e32 v141, 0
	v_mov_b32_e32 v83, 0
	s_and_saveexec_b64 s[0:1], s[40:41]
	s_cbranch_execz .LBB0_587
	v_mov_b32_e32 v71, v0
	v_mov_b32_e32 v80, v232
	v_mov_b32_e32 v81, v233
	v_mov_b32_e32 v82, v234
	v_mov_b32_e32 v83, v235
	v_mov_b32_e32 v139, v80
	v_mov_b32_e32 v141, v82
.LBB0_587:
	s_or_b64 exec, exec, s[0:1]
	v_mov_b32_e32 v90, 0
	v_mov_b32_e32 v91, 0
	v_mov_b32_e32 v77, 0
	s_and_saveexec_b64 s[0:1], s[40:41]
	s_cbranch_execz .LBB0_589
	v_mov_b32_e32 v71, v0
	v_mov_b32_e32 v76, v236
	v_mov_b32_e32 v77, v237
	v_mov_b32_e32 v78, v238
	v_mov_b32_e32 v79, v239
	v_mov_b32_e32 v90, v77
	v_mov_b32_e32 v91, v78
	v_mov_b32_e32 v77, v79
.LBB0_589:
	s_or_b64 exec, exec, s[0:1]
	v_mov_b32_e32 v68, 0
	v_mov_b32_e32 v72, 0
	v_mov_b32_e32 v73, 0
	v_mov_b32_e32 v74, 0
	v_mov_b32_e32 v75, 0
	s_and_saveexec_b64 s[0:1], s[40:41]
	s_cbranch_execz .LBB0_591
	v_mov_b32_e32 v71, v0
	v_mov_b32_e32 v72, v240
	v_mov_b32_e32 v73, v241
	v_mov_b32_e32 v74, v242
	v_mov_b32_e32 v75, v243
.LBB0_591:
	s_or_b64 exec, exec, s[0:1]
	v_mov_b32_e32 v69, 0
	v_mov_b32_e32 v79, 0
	v_mov_b32_e32 v71, 0
	s_and_saveexec_b64 s[0:1], s[40:41]
	s_cbranch_execz .LBB0_498
	v_mov_b32_e32 v71, v0
	v_mov_b32_e32 v68, v244
	v_mov_b32_e32 v69, v245
	v_mov_b32_e32 v70, v246
	v_mov_b32_e32 v71, v247
	v_mov_b32_e32 v79, v70
	s_branch .LBB0_498
